# alow gate-column rows: the four 16-load operand batches double-buffered over a second register set (two batches in flight)
# baseline (speedup 1.0000x reference)
; __device__ __forceinline__ void alow_rows(const bf16_t* YB, const bf16_t* Wal, const float* MUR, const float* cs, const float* cb, bf16_t* ALOW, int gw, int NGW, int lane) {
;     ...
;     for (int rb = gw; rb < M / 16; rb += NGW) {
;         const bf16_t* ap = YB + (size_t)(rb * 16 + i) * 1024 + 8 * kg; const bf16_t* wp = Wal + (size_t)i * 1024 + 8 * kg;
;         f32x4 acc0 = (f32x4){0.f, 0.f, 0.f, 0.f}, acc1 = acc0;
; #pragma unroll
;         for (int s0 = 0; s0 < 32; s0 += 8) { bf16x8_t af[8], wf[8];
; #pragma unroll
;             for (int s = 0; s < 8; ++s) { af[s] = *(const bf16x8_t*)(ap + 32 * (s0 + s)); wf[s] = *(const bf16x8_t*)(wp + 32 * (s0 + s)); }
; #pragma unroll
;             for (int s = 0; s < 8; s += 2) { acc0 = __builtin_amdgcn_mfma_f32_16x16x32_bf16(wf[s], af[s], acc0, 0, 0, 0); acc1 = __builtin_amdgcn_mfma_f32_16x16x32_bf16(wf[s + 1], af[s + 1], acc1, 0, 0, 0); } }
.LBB0_743:
	v_ashrrev_i32_e32 v11, 31, v10
	v_lshlrev_b64 v[12:13], 11, v[10:11]
	v_lshl_add_u64 v[12:13], v[0:1], 0, v[12:13]
	global_load_dwordx4 v[14:17], v[12:13], off
	global_load_dwordx4 v[18:21], v[2:3], off
	global_load_dwordx4 v[22:25], v[12:13], off offset:64
	global_load_dwordx4 v[26:29], v[2:3], off offset:64
	global_load_dwordx4 v[30:33], v[12:13], off offset:128
	global_load_dwordx4 v[34:37], v[2:3], off offset:128
	global_load_dwordx4 v[38:41], v[12:13], off offset:192
	global_load_dwordx4 v[42:45], v[2:3], off offset:192
	global_load_dwordx4 v[46:49], v[12:13], off offset:256
	global_load_dwordx4 v[50:53], v[2:3], off offset:256
	global_load_dwordx4 v[54:57], v[12:13], off offset:320
	global_load_dwordx4 v[58:61], v[2:3], off offset:320
	global_load_dwordx4 v[62:65], v[12:13], off offset:384
	global_load_dwordx4 v[66:69], v[2:3], off offset:384
	global_load_dwordx4 v[70:73], v[12:13], off offset:448
	global_load_dwordx4 v[74:77], v[2:3], off offset:448
	global_load_dwordx4 v[86:89], v[12:13], off offset:512
	global_load_dwordx4 v[90:93], v[2:3], off offset:512
	global_load_dwordx4 v[94:97], v[12:13], off offset:576
	global_load_dwordx4 v[98:101], v[2:3], off offset:576
	global_load_dwordx4 v[102:105], v[12:13], off offset:640
	global_load_dwordx4 v[106:109], v[2:3], off offset:640
	global_load_dwordx4 v[110:113], v[12:13], off offset:704
	global_load_dwordx4 v[114:117], v[2:3], off offset:704
	global_load_dwordx4 v[118:121], v[12:13], off offset:768
	global_load_dwordx4 v[122:125], v[2:3], off offset:768
	global_load_dwordx4 v[126:129], v[12:13], off offset:832
	global_load_dwordx4 v[130:133], v[2:3], off offset:832
	global_load_dwordx4 v[134:137], v[12:13], off offset:896
	global_load_dwordx4 v[138:141], v[2:3], off offset:896
	global_load_dwordx4 v[142:145], v[12:13], off offset:960
	global_load_dwordx4 v[146:149], v[2:3], off offset:960
	s_add_i32 s4, s4, s66
	s_cmpk_gt_i32 s4, 0x7ff
	s_waitcnt vmcnt(30)
	v_mfma_f32_16x16x32_bf16 v[14:17], v[18:21], v[14:17], 0
	s_waitcnt vmcnt(28)
	v_mfma_f32_16x16x32_bf16 v[18:21], v[26:29], v[22:25], 0
	s_waitcnt vmcnt(26)
	v_mfma_f32_16x16x32_bf16 v[14:17], v[34:37], v[30:33], v[14:17]
	s_waitcnt vmcnt(24)
	v_mfma_f32_16x16x32_bf16 v[18:21], v[42:45], v[38:41], v[18:21]
	s_waitcnt vmcnt(22)
	v_mfma_f32_16x16x32_bf16 v[14:17], v[50:53], v[46:49], v[14:17]
	s_waitcnt vmcnt(20)
	v_mfma_f32_16x16x32_bf16 v[18:21], v[58:61], v[54:57], v[18:21]
	s_waitcnt vmcnt(18)
	v_mfma_f32_16x16x32_bf16 v[14:17], v[66:69], v[62:65], v[14:17]
	s_waitcnt vmcnt(16)
	v_mfma_f32_16x16x32_bf16 v[18:21], v[74:77], v[70:73], v[18:21]
	global_load_dwordx4 v[22:25], v[12:13], off offset:1024
	global_load_dwordx4 v[26:29], v[2:3], off offset:1024
	global_load_dwordx4 v[30:33], v[12:13], off offset:1088
	global_load_dwordx4 v[34:37], v[2:3], off offset:1088
	global_load_dwordx4 v[38:41], v[12:13], off offset:1152
	global_load_dwordx4 v[42:45], v[2:3], off offset:1152
	global_load_dwordx4 v[46:49], v[12:13], off offset:1216
	global_load_dwordx4 v[50:53], v[2:3], off offset:1216
	global_load_dwordx4 v[54:57], v[12:13], off offset:1280
	global_load_dwordx4 v[58:61], v[2:3], off offset:1280
	global_load_dwordx4 v[62:65], v[12:13], off offset:1344
	global_load_dwordx4 v[66:69], v[2:3], off offset:1344
	global_load_dwordx4 v[70:73], v[12:13], off offset:1408
	global_load_dwordx4 v[74:77], v[2:3], off offset:1408
	global_load_dwordx4 v[78:81], v[12:13], off offset:1472
	global_load_dwordx4 v[82:85], v[2:3], off offset:1472
	s_waitcnt vmcnt(30)
	v_mfma_f32_16x16x32_bf16 v[14:17], v[90:93], v[86:89], v[14:17]
	s_waitcnt vmcnt(28)
	v_mfma_f32_16x16x32_bf16 v[18:21], v[98:101], v[94:97], v[18:21]
	s_waitcnt vmcnt(26)
	v_mfma_f32_16x16x32_bf16 v[14:17], v[106:109], v[102:105], v[14:17]
	s_waitcnt vmcnt(24)
	v_mfma_f32_16x16x32_bf16 v[18:21], v[114:117], v[110:113], v[18:21]
	s_waitcnt vmcnt(22)
; __device__ __forceinline__ unsigned pk2(float lo, float hi) { return (unsigned)f2bf(lo) | ((unsigned)f2bf(hi) << 16); }
; __device__ __forceinline__ void alow_rows(const bf16_t* YB, const bf16_t* Wal, const float* MUR, const float* cs, const float* cb, bf16_t* ALOW, int gw, int NGW, int lane) {
;     ...
;         for (int s0 = 0; s0 < 32; s0 += 8) { bf16x8_t af[8], wf[8];
; #pragma unroll
;             for (int s = 0; s < 8; ++s) { af[s] = *(const bf16x8_t*)(ap + 32 * (s0 + s)); wf[s] = *(const bf16x8_t*)(wp + 32 * (s0 + s)); }
; #pragma unroll
;             for (int s = 0; s < 8; s += 2) { acc0 = __builtin_amdgcn_mfma_f32_16x16x32_bf16(wf[s], af[s], acc0, 0, 0, 0); acc1 = __builtin_amdgcn_mfma_f32_16x16x32_bf16(wf[s + 1], af[s + 1], acc1, 0, 0, 0); } }
;         const float mu = MUR[2 * (size_t)(rb * 16 + i)], rs = MUR[2 * (size_t)(rb * 16 + i) + 1];
;         const f32x4 c4 = *(const f32x4*)(cs + 4 * kg), b4 = *(const f32x4*)(cb + 4 * kg);
;         const f32x4 z = ((acc0 + acc1) - c4 * mu) * rs + b4;
;         u32x2_t w; w.x = pk2(z[0], z[1]); w.y = pk2(z[2], z[3]);
;         *(u32x2_t*)(ALOW + (size_t)(rb * 16 + i) * 16 + 4 * kg) = w;
;     }
	v_mfma_f32_16x16x32_bf16 v[14:17], v[122:125], v[118:121], v[14:17]
	s_waitcnt vmcnt(20)
	v_mfma_f32_16x16x32_bf16 v[18:21], v[130:133], v[126:129], v[18:21]
	s_waitcnt vmcnt(18)
	v_mfma_f32_16x16x32_bf16 v[14:17], v[138:141], v[134:137], v[14:17]
	s_waitcnt vmcnt(16)
	v_mfma_f32_16x16x32_bf16 v[18:21], v[146:149], v[142:145], v[18:21]
	global_load_dwordx4 v[86:89], v[12:13], off offset:1536
	global_load_dwordx4 v[90:93], v[2:3], off offset:1536
	global_load_dwordx4 v[94:97], v[12:13], off offset:1600
	global_load_dwordx4 v[98:101], v[2:3], off offset:1600
	global_load_dwordx4 v[102:105], v[12:13], off offset:1664
	global_load_dwordx4 v[106:109], v[2:3], off offset:1664
	global_load_dwordx4 v[110:113], v[12:13], off offset:1728
	global_load_dwordx4 v[114:117], v[2:3], off offset:1728
	global_load_dwordx4 v[118:121], v[12:13], off offset:1792
	global_load_dwordx4 v[122:125], v[2:3], off offset:1792
	global_load_dwordx4 v[126:129], v[12:13], off offset:1856
	global_load_dwordx4 v[130:133], v[2:3], off offset:1856
	global_load_dwordx4 v[134:137], v[12:13], off offset:1920
	global_load_dwordx4 v[138:141], v[2:3], off offset:1920
	global_load_dwordx4 v[142:145], v[12:13], off offset:1984
	global_load_dwordx4 v[146:149], v[2:3], off offset:1984
	s_waitcnt vmcnt(30)
	v_mfma_f32_16x16x32_bf16 v[14:17], v[26:29], v[22:25], v[14:17]
	s_waitcnt vmcnt(28)
	v_mfma_f32_16x16x32_bf16 v[18:21], v[34:37], v[30:33], v[18:21]
	s_waitcnt vmcnt(26)
	v_mfma_f32_16x16x32_bf16 v[14:17], v[42:45], v[38:41], v[14:17]
	s_waitcnt vmcnt(24)
	v_mfma_f32_16x16x32_bf16 v[18:21], v[50:53], v[46:49], v[18:21]
	s_waitcnt vmcnt(22)
	v_mfma_f32_16x16x32_bf16 v[14:17], v[58:61], v[54:57], v[14:17]
	s_waitcnt vmcnt(20)
	v_mfma_f32_16x16x32_bf16 v[18:21], v[66:69], v[62:65], v[18:21]
	s_waitcnt vmcnt(18)
	v_mfma_f32_16x16x32_bf16 v[14:17], v[74:77], v[70:73], v[14:17]
	s_waitcnt vmcnt(16)
	v_mfma_f32_16x16x32_bf16 v[18:21], v[82:85], v[78:81], v[18:21]
	s_waitcnt vmcnt(14)
	v_mfma_f32_16x16x32_bf16 v[12:15], v[90:93], v[86:89], v[14:17]
	s_waitcnt vmcnt(12)
	v_mfma_f32_16x16x32_bf16 v[16:19], v[98:101], v[94:97], v[18:21]
	s_nop 2
	v_lshl_add_u64 v[20:21], v[10:11], 3, s[88:89]
	global_load_dwordx2 v[28:29], v[20:21], off
	s_nop 0
	global_load_dwordx4 v[20:23], v[4:5], off
	global_load_dwordx4 v[24:27], v[6:7], off
	s_waitcnt vmcnt(13)
	v_mfma_f32_16x16x32_bf16 v[12:15], v[106:109], v[102:105], v[12:15]
	s_waitcnt vmcnt(11)
	v_mfma_f32_16x16x32_bf16 v[16:19], v[114:117], v[110:113], v[16:19]
	s_waitcnt vmcnt(9)
	v_mfma_f32_16x16x32_bf16 v[12:15], v[122:125], v[118:121], v[12:15]
	s_waitcnt vmcnt(7)
	v_mfma_f32_16x16x32_bf16 v[16:19], v[130:133], v[126:129], v[16:19]
	s_waitcnt vmcnt(5)
	v_mfma_f32_16x16x32_bf16 v[12:15], v[138:141], v[134:137], v[12:15]
	s_waitcnt vmcnt(3)
	v_mfma_f32_16x16x32_bf16 v[16:19], v[146:149], v[142:145], v[16:19]
	s_nop 7
	v_pk_add_f32 v[12:13], v[12:13], v[16:17]
	v_pk_add_f32 v[14:15], v[14:15], v[18:19]
	s_waitcnt vmcnt(1)
	v_pk_fma_f32 v[12:13], v[20:21], v[28:29], v[12:13] op_sel_hi:[1,0,1] neg_lo:[1,0,0] neg_hi:[1,0,0]
	v_xor_b32_e32 v17, 0x80000000, v23
	v_xor_b32_e32 v16, 0x80000000, v22
	s_waitcnt vmcnt(0)
	v_pk_fma_f32 v[12:13], v[28:29], v[12:13], v[24:25] op_sel:[1,0,0]
	v_pk_fma_f32 v[14:15], v[16:17], v[28:29], v[14:15] op_sel_hi:[1,0,1]
	v_bfe_u32 v16, v12, 16, 1
	v_add3_u32 v12, v12, v16, s67
	v_bfe_u32 v16, v13, 16, 1
	v_pk_fma_f32 v[14:15], v[28:29], v[14:15], v[26:27] op_sel:[1,0,0]
	v_lshrrev_b32_e32 v12, 16, v12
	v_add3_u32 v13, v13, v16, s67
	v_and_or_b32 v12, v13, s57, v12
	v_bfe_u32 v13, v14, 16, 1
	v_add3_u32 v13, v14, v13, s67
	v_bfe_u32 v14, v15, 16, 1
	v_lshrrev_b32_e32 v13, 16, v13
	v_add3_u32 v14, v15, v14, s67
	v_and_or_b32 v13, v14, s57, v13
	v_lshlrev_b64 v[14:15], 5, v[10:11]
	v_lshl_add_u64 v[14:15], v[8:9], 0, v[14:15]
	v_add_u32_e32 v10, s6, v10
	global_store_dwordx2 v[14:15], v[12:13], off
	s_cbranch_scc0 .LBB0_743
